# phases 8 and 18 CU-partner offset 6 us
# speedup vs baseline: 1.0046x; 1.0046x over previous
.LBB0_491:
	s_getreg_b32 s98, hwreg(HW_REG_HW_ID, 0, 4)
	s_cmp_eq_u32 s98, 0
	s_cbranch_scc1 .Lstg0_done
	s_memrealtime s[98:99]
	s_waitcnt lgkmcnt(0)
	s_add_u32 s98, s98, 600
